# grid barriers 2-5 hand-written: XCD leader arrives at the top counter with a plain atomic, all CUs poll the cumulative top counter (no second returning atomic, no generation word hop)
# speedup vs baseline: 1.1300x; 1.0070x over previous
; __device__ __forceinline__ unsigned xb_add(unsigned* p, unsigned v) { return __hip_atomic_fetch_add(p, v, __ATOMIC_RELAXED, __HIP_MEMORY_SCOPE_AGENT); }
; __device__ __forceinline__ XbState xcd_barrier_arrive(const XcdBarrier& b) {
;     asm volatile("s_waitcnt vmcnt(0)" ::: "memory");
;     __syncthreads();
;     unsigned* bar = b.bar;
;     XbState st; st.gen = 0u; st.tg = 0u; st.lastx = false; st.lastt = false;
;     if (threadIdx.x == 0) {
;         __builtin_amdgcn_s_waitcnt(0);
;         unsigned nloc = b.st[0], nx = b.st[1];
;         if (nloc == 0u) { xcd_barrier_complete(bar, b.x, nloc, nx); b.st[0] = nloc; b.st[1] = nx; }
;         const unsigned old = xb_add(&bar[XB_XSUB(b.x)], 1u);
;         st.gen = old / nloc; st.lastx = (old + 1u == (st.gen + 1u) * nloc);
;         if (st.lastx) {
;             __builtin_amdgcn_fence(__ATOMIC_RELEASE, "agent");
;             asm volatile("s_waitcnt vmcnt(0)" ::: "memory");
;             const unsigned og = xb_add(&bar[XB_TOP], 1u);
;             st.tg = og / nx; st.lastt = (og + 1u == (st.tg + 1u) * nx);
;             if (st.lastt) xb_add(&bar[XB_TOPGEN], 1u);
;         }
;     }
.Lside_done:
	s_waitcnt vmcnt(0)
	v_mov_b32_e32 v3, 0
	s_mov_b64 s[8:9], 0
	s_waitcnt lgkmcnt(0)
	s_mov_b64 s[6:7], 0
	v_mov_b32_e32 v2, 0
	s_waitcnt vmcnt(0)
	s_barrier
	s_and_saveexec_b64 s[4:5], s[14:15]
	s_cbranch_execz .LBB0_382
	s_waitcnt vmcnt(0) lgkmcnt(0)
	v_mov_b32_e32 v1, 0x27c20
	ds_read_b32 v3, v1
	ds_read_b32 v4, v1 offset:4
	buffer_inv sc1
	s_lshl_b32 s8, s33, 8
	s_add_u32 s8, s82, s8
	s_addc_u32 s9, s83, 0
	v_mov_b32_e32 v1, 0x1000
	v_mov_b32_e32 v5, 1
	global_atomic_add v6, v1, v5, s[8:9] offset:1024 sc0
	s_waitcnt vmcnt(0) lgkmcnt(0)
	v_add_u32_e32 v6, 1, v6
	v_mul_u32_u24_e32 v7, 2, v3
	v_mul_u32_u24_e32 v2, 2, v4
	v_cmp_eq_u32_e32 vcc, v6, v7
	s_and_saveexec_b64 s[8:9], vcc
	s_cbranch_execz .Lbar2_notlast
	buffer_wbl2 sc1
	s_waitcnt vmcnt(0)
	v_mov_b32_e32 v1, 0x7000
	global_atomic_add v1, v5, s[30:31] offset:1024
.Lbar2_notlast:
	s_or_b64 exec, exec, s[8:9]


; __device__ __forceinline__ unsigned xb_ld(unsigned* p)              { return __hip_atomic_load(p, __ATOMIC_RELAXED, __HIP_MEMORY_SCOPE_AGENT); }
; #define XB_SPIN(cond, bar) do { unsigned _sp = 0; while (cond) { __builtin_amdgcn_s_sleep(1); \
;     if ((++_sp & 255u) == 0u) { if (xb_ld(&(bar)[XB_TMO])) break; if (_sp > XB_SPIN_CAP) { atomicAdd(&(bar)[XB_TMO], 1u); break; } } } } while (0)
; __device__ __forceinline__ void xcd_barrier_wait(const XcdBarrier& b, const XbState& st) {
;     unsigned* bar = b.bar;
;     if (threadIdx.x == 0) {
;         if (st.lastx) {
;             if (!st.lastt) XB_SPIN(xb_ld(&bar[XB_TOPGEN]) == st.tg, bar);
;             __builtin_amdgcn_fence(__ATOMIC_ACQUIRE, "agent");
;             asm volatile("s_waitcnt vmcnt(0)" ::: "memory");
;         } else {
;             XB_SPIN(xb_ld(&bar[XB_TOPGEN]) == st.gen, bar);
;             __builtin_amdgcn_fence(__ATOMIC_ACQUIRE, "agent");
;             asm volatile("s_waitcnt vmcnt(0)" ::: "memory");
;         }
; __global__ void __launch_bounds__(NTHR, 2) hybrid_fwd(Args args) {
;     ...
;     ConvW cw;
;     { const XbState xs = xcd_barrier_arrive(bar);
;       unsigned ln = threadIdx.x & 63u; asm volatile("" : "+v"(ln)); const unsigned wv = threadIdx.x >> 6;
;       const unsigned p = 192u * wv + 2u * ln, q = 192u * wv + 128u + ln; const float* w = args.in[14]; const float* bb = args.in[15];
; #pragma unroll
;       for (int j = 0; j < CW; ++j) { cw.wp[j] = ldg<f32x2>(w + (size_t)j * DCONV, p * 4u); cw.wq[j] = ldg<float>(w + (size_t)j * DCONV, q * 4u); }
;       cw.bp = ldg<f32x2>(bb, p * 4u); cw.bq = ldg<float>(bb, q * 4u);
;       xcd_barrier_wait(bar, xs); }
.LBB0_382:
	s_or_b64 exec, exec, s[4:5]
	s_add_u32 s10, s24, 0x1800
	s_waitcnt lgkmcnt(0)
	v_and_b32_e32 v1, 63, v0
	v_lshrrev_b32_e32 v5, 6, v0
	s_movk_i32 s4, 0xc0
	s_addc_u32 s11, s25, 0
	s_nop 0
	v_mad_u32_u24 v4, v5, s4, v1
	s_add_u32 s4, s24, 0x3000
	s_addc_u32 s5, s25, 0
	s_add_u32 s16, s24, 0x4800
	s_addc_u32 s17, s25, 0
	s_add_u32 s18, s24, 0x6000
	s_addc_u32 s19, s25, 0
	s_add_u32 s22, s24, 0x7800
	s_addc_u32 s23, s25, 0
	s_add_u32 s20, s24, 0x9000
	s_addc_u32 s21, s25, 0
	s_add_u32 s12, s24, 0xa800
	s_addc_u32 s13, s25, 0
	s_add_u32 s34, s24, 0xc000
	s_addc_u32 s35, s25, 0
	s_add_u32 s36, s24, 0xd800
	s_addc_u32 s37, s25, 0
	s_add_u32 s38, s24, 0xf000
	s_addc_u32 s39, s25, 0
	s_add_u32 s40, s24, 0x10800
	s_addc_u32 s41, s25, 0
	s_add_u32 s42, s24, 0x12000
	s_addc_u32 s43, s25, 0
	s_add_u32 s44, s24, 0x13800
	s_addc_u32 s45, s25, 0
	v_mul_u32_u24_e32 v5, 0x300, v5
	s_add_u32 s46, s24, 0x15000
	v_lshl_add_u32 v1, v1, 3, v5
	v_mov_b32_e32 v5, 0x200
	s_addc_u32 s47, s25, 0
	v_lshl_add_u32 v4, v4, 2, v5
	global_load_dwordx2 v[58:59], v1, s[16:17]
	global_load_dwordx2 v[60:61], v1, s[18:19]
	global_load_dwordx2 v[62:63], v1, s[22:23]
	global_load_dwordx2 v[64:65], v1, s[20:21]
	global_load_dwordx2 v[66:67], v1, s[12:13]
	global_load_dwordx2 v[68:69], v1, s[34:35]
	global_load_dwordx2 v[70:71], v1, s[36:37]
	global_load_dwordx2 v[72:73], v1, s[38:39]
	global_load_dwordx2 v[74:75], v1, s[40:41]
	global_load_dwordx2 v[76:77], v1, s[42:43]
	global_load_dwordx2 v[78:79], v1, s[44:45]
	global_load_dwordx2 v[80:81], v1, s[46:47]
	global_load_dword v166, v4, s[12:13]
	global_load_dword v167, v4, s[34:35]
	global_load_dword v168, v4, s[36:37]
	global_load_dword v169, v4, s[38:39]
	global_load_dword v170, v4, s[40:41]
	global_load_dword v171, v4, s[42:43]
	global_load_dword v172, v4, s[44:45]
	global_load_dword v173, v4, s[46:47]
	s_add_u32 s12, s24, 0x16800
	s_addc_u32 s13, s25, 0
	s_add_u32 s34, s24, 0x18000
	s_addc_u32 s35, s25, 0
	s_add_u32 s36, s24, 0x19800
	s_addc_u32 s37, s25, 0
	s_add_u32 s38, s24, 0x1b000
	s_addc_u32 s39, s25, 0
	s_add_u32 s40, s24, 0x1c800
	s_addc_u32 s41, s25, 0
	s_add_u32 s42, s24, 0x1e000
	s_addc_u32 s43, s25, 0
	s_add_u32 s44, s24, 0x1f800
	s_addc_u32 s45, s25, 0
	s_add_u32 s46, s24, 0x21000
	s_addc_u32 s47, s25, 0
	global_load_dwordx2 v[82:83], v1, s[12:13]
	global_load_dwordx2 v[84:85], v1, s[34:35]
	global_load_dwordx2 v[86:87], v1, s[36:37]
	global_load_dwordx2 v[88:89], v1, s[38:39]
	global_load_dwordx2 v[90:91], v1, s[40:41]
	global_load_dwordx2 v[92:93], v1, s[42:43]
	global_load_dwordx2 v[94:95], v1, s[44:45]
	global_load_dwordx2 v[96:97], v1, s[46:47]
	global_load_dword v174, v4, s[12:13]
	global_load_dword v175, v4, s[34:35]
	global_load_dword v176, v4, s[36:37]
	global_load_dword v177, v4, s[38:39]
	global_load_dword v178, v4, s[40:41]
	global_load_dword v179, v4, s[42:43]
	global_load_dword v180, v4, s[44:45]
	global_load_dword v181, v4, s[46:47]
	s_add_u32 s12, s24, 0x22800
	s_addc_u32 s13, s25, 0
	s_add_u32 s34, s24, 0x24000
	s_addc_u32 s35, s25, 0
	s_add_u32 s36, s24, 0x25800
	s_addc_u32 s37, s25, 0
	s_add_u32 s38, s24, 0x27000
	s_addc_u32 s39, s25, 0
	s_add_u32 s40, s24, 0x28800
	s_addc_u32 s41, s25, 0
	s_add_u32 s42, s24, 0x2a000
	s_addc_u32 s43, s25, 0
	s_add_u32 s44, s24, 0x2b800
	s_addc_u32 s45, s25, 0
	s_add_u32 s46, s24, 0x2d000
	global_load_dwordx2 v[98:99], v1, s[12:13]
	global_load_dwordx2 v[100:101], v1, s[34:35]
	global_load_dwordx2 v[102:103], v1, s[36:37]
	global_load_dwordx2 v[104:105], v1, s[38:39]
	s_addc_u32 s47, s25, 0
	global_load_dwordx2 v[106:107], v1, s[40:41]
	global_load_dwordx2 v[108:109], v1, s[42:43]
	global_load_dwordx2 v[110:111], v1, s[44:45]
	global_load_dwordx2 v[112:113], v1, s[46:47]
	global_load_dword v182, v4, s[12:13]
	global_load_dword v183, v4, s[34:35]
	global_load_dword v184, v4, s[36:37]
	global_load_dword v185, v4, s[38:39]
	global_load_dword v186, v4, s[40:41]
	global_load_dword v187, v4, s[42:43]
	global_load_dword v188, v4, s[44:45]
	global_load_dword v189, v4, s[46:47]
	global_load_dwordx2 v[114:115], v1, s[24:25]
	global_load_dwordx2 v[116:117], v1, s[10:11]
	global_load_dwordx2 v[118:119], v1, s[4:5]
	global_load_dwordx2 v[120:121], v1, s[26:27]
	global_load_dword v190, v4, s[24:25]
	global_load_dword v191, v4, s[10:11]
	global_load_dword v192, v4, s[4:5]
	global_load_dword v193, v4, s[16:17]
	global_load_dword v194, v4, s[18:19]
	global_load_dword v195, v4, s[22:23]
	global_load_dword v196, v4, s[20:21]
	global_load_dword v197, v4, s[26:27]
	s_and_saveexec_b64 s[4:5], s[14:15]
	s_cbranch_execz .LBB0_412
	v_mov_b32_e32 v1, 0x7000
	s_mov_b32 s16, 0
.Lbar2_poll:
	global_load_dword v3, v1, s[30:31] offset:1024 sc1
	s_waitcnt vmcnt(0)
	v_cmp_ge_u32_e32 vcc, v3, v2
	s_cbranch_vccnz .Lbar2_go
	s_sleep 1
	s_add_u32 s16, s16, 1
	s_cmp_lt_u32 s16, 0x8000
	s_cbranch_scc1 .Lbar2_poll
.Lbar2_go:



; __device__ __forceinline__ unsigned xb_add(unsigned* p, unsigned v) { return __hip_atomic_fetch_add(p, v, __ATOMIC_RELAXED, __HIP_MEMORY_SCOPE_AGENT); }
; __device__ __forceinline__ XbState xcd_barrier_arrive(const XcdBarrier& b) {
;     asm volatile("s_waitcnt vmcnt(0)" ::: "memory");
;     __syncthreads();
;     unsigned* bar = b.bar;
;     XbState st; st.gen = 0u; st.tg = 0u; st.lastx = false; st.lastt = false;
;     if (threadIdx.x == 0) {
;         __builtin_amdgcn_s_waitcnt(0);
;         unsigned nloc = b.st[0], nx = b.st[1];
;         if (nloc == 0u) { xcd_barrier_complete(bar, b.x, nloc, nx); b.st[0] = nloc; b.st[1] = nx; }
;         const unsigned old = xb_add(&bar[XB_XSUB(b.x)], 1u);
;         st.gen = old / nloc; st.lastx = (old + 1u == (st.gen + 1u) * nloc);
;         if (st.lastx) {
;             __builtin_amdgcn_fence(__ATOMIC_RELEASE, "agent");
;             asm volatile("s_waitcnt vmcnt(0)" ::: "memory");
;             const unsigned og = xb_add(&bar[XB_TOP], 1u);
;             st.tg = og / nx; st.lastt = (og + 1u == (st.tg + 1u) * nx);
;             if (st.lastt) xb_add(&bar[XB_TOPGEN], 1u);
;         }
;     }
.LBB0_565:
	s_waitcnt vmcnt(0)
	v_mov_b32_e32 v3, 0
	s_waitcnt lgkmcnt(0)
	s_mov_b64 s[16:17], 0
	s_mov_b64 s[8:9], 0
	v_mov_b32_e32 v2, 0
	s_barrier
	s_and_saveexec_b64 s[6:7], s[14:15]
	s_cbranch_execz .LBB0_592
	s_waitcnt vmcnt(0) lgkmcnt(0)
	v_mov_b32_e32 v1, 0x27c20
	ds_read_b32 v3, v1
	ds_read_b32 v4, v1 offset:4
	buffer_inv sc1
	s_lshl_b32 s8, s33, 8
	s_add_u32 s8, s82, s8
	s_addc_u32 s9, s83, 0
	v_mov_b32_e32 v1, 0x1000
	v_mov_b32_e32 v5, 1
	global_atomic_add v6, v1, v5, s[8:9] offset:1024 sc0
	s_waitcnt vmcnt(0) lgkmcnt(0)
	v_add_u32_e32 v6, 1, v6
	v_mul_u32_u24_e32 v7, 3, v3
	v_mul_u32_u24_e32 v2, 3, v4
	v_cmp_eq_u32_e32 vcc, v6, v7
	s_and_saveexec_b64 s[8:9], vcc
	s_cbranch_execz .Lbar3_notlast
	buffer_wbl2 sc1
	s_waitcnt vmcnt(0)
	v_mov_b32_e32 v1, 0x7000
	global_atomic_add v1, v5, s[30:31] offset:1024

; __device__ __forceinline__ unsigned xb_ld(unsigned* p)              { return __hip_atomic_load(p, __ATOMIC_RELAXED, __HIP_MEMORY_SCOPE_AGENT); }
; #define XB_SPIN(cond, bar) do { unsigned _sp = 0; while (cond) { __builtin_amdgcn_s_sleep(1); \
;     if ((++_sp & 255u) == 0u) { if (xb_ld(&(bar)[XB_TMO])) break; if (_sp > XB_SPIN_CAP) { atomicAdd(&(bar)[XB_TMO], 1u); break; } } } } while (0)
; __device__ __forceinline__ void xcd_barrier_wait(const XcdBarrier& b, const XbState& st) {
;     unsigned* bar = b.bar;
;     if (threadIdx.x == 0) {
;         if (st.lastx) {
;             if (!st.lastt) XB_SPIN(xb_ld(&bar[XB_TOPGEN]) == st.tg, bar);
;             __builtin_amdgcn_fence(__ATOMIC_ACQUIRE, "agent");
;             asm volatile("s_waitcnt vmcnt(0)" ::: "memory");
;         } else {
;             XB_SPIN(xb_ld(&bar[XB_TOPGEN]) == st.gen, bar);
;             __builtin_amdgcn_fence(__ATOMIC_ACQUIRE, "agent");
;             asm volatile("s_waitcnt vmcnt(0)" ::: "memory");
;         }
.LBB0_598:
	s_and_saveexec_b64 s[12:13], s[14:15]
	s_cbranch_execz .LBB0_628
	v_mov_b32_e32 v1, 0x7000
	s_mov_b32 s16, 0

; __device__ __forceinline__ unsigned xb_add(unsigned* p, unsigned v) { return __hip_atomic_fetch_add(p, v, __ATOMIC_RELAXED, __HIP_MEMORY_SCOPE_AGENT); }
; __device__ __forceinline__ XbState xcd_barrier_arrive(const XcdBarrier& b) {
;     asm volatile("s_waitcnt vmcnt(0)" ::: "memory");
;     __syncthreads();
;     unsigned* bar = b.bar;
;     XbState st; st.gen = 0u; st.tg = 0u; st.lastx = false; st.lastt = false;
;     if (threadIdx.x == 0) {
;         __builtin_amdgcn_s_waitcnt(0);
;         unsigned nloc = b.st[0], nx = b.st[1];
;         if (nloc == 0u) { xcd_barrier_complete(bar, b.x, nloc, nx); b.st[0] = nloc; b.st[1] = nx; }
;         const unsigned old = xb_add(&bar[XB_XSUB(b.x)], 1u);
;         st.gen = old / nloc; st.lastx = (old + 1u == (st.gen + 1u) * nloc);
;         if (st.lastx) {
;             __builtin_amdgcn_fence(__ATOMIC_RELEASE, "agent");
;             asm volatile("s_waitcnt vmcnt(0)" ::: "memory");
;             const unsigned og = xb_add(&bar[XB_TOP], 1u);
;             st.tg = og / nx; st.lastt = (og + 1u == (st.tg + 1u) * nx);
;             if (st.lastt) xb_add(&bar[XB_TOPGEN], 1u);
;         }
;     }
.LBB0_670:
	s_waitcnt vmcnt(0)
	v_mov_b32_e32 v3, 0
	s_mov_b64 s[16:17], 0
	s_mov_b64 s[8:9], 0
	v_mov_b32_e32 v2, 0
	s_barrier
	s_and_saveexec_b64 s[6:7], s[14:15]
	s_cbranch_execz .LBB0_697
	s_waitcnt vmcnt(0) lgkmcnt(0)
	v_mov_b32_e32 v1, 0x27c20
	ds_read_b32 v3, v1
	ds_read_b32 v4, v1 offset:4
	buffer_inv sc1
	s_lshl_b32 s8, s33, 8
	s_add_u32 s8, s82, s8
	s_addc_u32 s9, s83, 0
	v_mov_b32_e32 v1, 0x1000
	v_mov_b32_e32 v5, 1
	global_atomic_add v6, v1, v5, s[8:9] offset:1024 sc0
	s_waitcnt vmcnt(0) lgkmcnt(0)
	v_add_u32_e32 v6, 1, v6
	v_mul_u32_u24_e32 v7, 4, v3
	v_mul_u32_u24_e32 v2, 4, v4
	v_cmp_eq_u32_e32 vcc, v6, v7
	s_and_saveexec_b64 s[8:9], vcc
	s_cbranch_execz .Lbar4_notlast
	buffer_wbl2 sc1
	s_waitcnt vmcnt(0)
	v_mov_b32_e32 v1, 0x7000
	global_atomic_add v1, v5, s[30:31] offset:1024

; __device__ __forceinline__ unsigned xb_ld(unsigned* p)              { return __hip_atomic_load(p, __ATOMIC_RELAXED, __HIP_MEMORY_SCOPE_AGENT); }
; #define XB_SPIN(cond, bar) do { unsigned _sp = 0; while (cond) { __builtin_amdgcn_s_sleep(1); \
;     if ((++_sp & 255u) == 0u) { if (xb_ld(&(bar)[XB_TMO])) break; if (_sp > XB_SPIN_CAP) { atomicAdd(&(bar)[XB_TMO], 1u); break; } } } } while (0)
; __device__ __forceinline__ void xcd_barrier_wait(const XcdBarrier& b, const XbState& st) {
;     unsigned* bar = b.bar;
;     if (threadIdx.x == 0) {
;         if (st.lastx) {
;             if (!st.lastt) XB_SPIN(xb_ld(&bar[XB_TOPGEN]) == st.tg, bar);
;             __builtin_amdgcn_fence(__ATOMIC_ACQUIRE, "agent");
;             asm volatile("s_waitcnt vmcnt(0)" ::: "memory");
;         } else {
;             XB_SPIN(xb_ld(&bar[XB_TOPGEN]) == st.gen, bar);
;             __builtin_amdgcn_fence(__ATOMIC_ACQUIRE, "agent");
;             asm volatile("s_waitcnt vmcnt(0)" ::: "memory");
;         }
.LBB0_710:
	v_mov_b32_e32 v1, 0x7000
	s_mov_b32 s16, 0

; __device__ __forceinline__ unsigned xb_add(unsigned* p, unsigned v) { return __hip_atomic_fetch_add(p, v, __ATOMIC_RELAXED, __HIP_MEMORY_SCOPE_AGENT); }
; __device__ __forceinline__ XbState xcd_barrier_arrive(const XcdBarrier& b) {
;     asm volatile("s_waitcnt vmcnt(0)" ::: "memory");
;     __syncthreads();
;     unsigned* bar = b.bar;
;     XbState st; st.gen = 0u; st.tg = 0u; st.lastx = false; st.lastt = false;
;     if (threadIdx.x == 0) {
;         __builtin_amdgcn_s_waitcnt(0);
;         unsigned nloc = b.st[0], nx = b.st[1];
;         if (nloc == 0u) { xcd_barrier_complete(bar, b.x, nloc, nx); b.st[0] = nloc; b.st[1] = nx; }
;         const unsigned old = xb_add(&bar[XB_XSUB(b.x)], 1u);
;         st.gen = old / nloc; st.lastx = (old + 1u == (st.gen + 1u) * nloc);
;         if (st.lastx) {
;             __builtin_amdgcn_fence(__ATOMIC_RELEASE, "agent");
;             asm volatile("s_waitcnt vmcnt(0)" ::: "memory");
;             const unsigned og = xb_add(&bar[XB_TOP], 1u);
;             st.tg = og / nx; st.lastt = (og + 1u == (st.tg + 1u) * nx);
;             if (st.lastt) xb_add(&bar[XB_TOPGEN], 1u);
;         }
;     }
.LBB0_772:
	s_waitcnt vmcnt(0)
	v_mov_b32_e32 v67, 0
	s_mov_b64 s[10:11], 0
	s_mov_b64 s[8:9], 0
	v_mov_b32_e32 v66, 0
	s_waitcnt vmcnt(0)
	s_barrier
	s_and_saveexec_b64 s[6:7], s[14:15]
	s_cbranch_execz .LBB0_799
	s_waitcnt vmcnt(0) lgkmcnt(0)
	v_mov_b32_e32 v3, 0x27c20
	ds_read_b32 v1, v3
	ds_read_b32 v2, v3 offset:4
	buffer_inv sc1
	s_lshl_b32 s8, s33, 8
	s_add_u32 s8, s82, s8
	s_addc_u32 s9, s83, 0
	v_mov_b32_e32 v3, 0x1000
	v_mov_b32_e32 v4, 1
	global_atomic_add v5, v3, v4, s[8:9] offset:1024 sc0
	s_waitcnt vmcnt(0) lgkmcnt(0)
	v_add_u32_e32 v5, 1, v5
	v_mul_u32_u24_e32 v6, 5, v1
	v_mul_u32_u24_e32 v66, 5, v2
	v_cmp_eq_u32_e32 vcc, v5, v6
	s_and_saveexec_b64 s[8:9], vcc
	s_cbranch_execz .Lbar5_notlast
	buffer_wbl2 sc1
	s_waitcnt vmcnt(0)
	v_mov_b32_e32 v3, 0x7000
	global_atomic_add v3, v4, s[30:31] offset:1024

; __device__ __forceinline__ unsigned xb_ld(unsigned* p)              { return __hip_atomic_load(p, __ATOMIC_RELAXED, __HIP_MEMORY_SCOPE_AGENT); }
; #define XB_SPIN(cond, bar) do { unsigned _sp = 0; while (cond) { __builtin_amdgcn_s_sleep(1); \
;     if ((++_sp & 255u) == 0u) { if (xb_ld(&(bar)[XB_TMO])) break; if (_sp > XB_SPIN_CAP) { atomicAdd(&(bar)[XB_TMO], 1u); break; } } } } while (0)
; __device__ __forceinline__ void xcd_barrier_wait(const XcdBarrier& b, const XbState& st) {
;     unsigned* bar = b.bar;
;     if (threadIdx.x == 0) {
;         if (st.lastx) {
;             if (!st.lastt) XB_SPIN(xb_ld(&bar[XB_TOPGEN]) == st.tg, bar);
;             __builtin_amdgcn_fence(__ATOMIC_ACQUIRE, "agent");
;             asm volatile("s_waitcnt vmcnt(0)" ::: "memory");
;         } else {
;             XB_SPIN(xb_ld(&bar[XB_TOPGEN]) == st.gen, bar);
;             __builtin_amdgcn_fence(__ATOMIC_ACQUIRE, "agent");
;             asm volatile("s_waitcnt vmcnt(0)" ::: "memory");
;         }
; __global__ void __launch_bounds__(NTHR, 2) hybrid_fwd(Args args) {
;     ...
;     f32x4 xpre[16];
;     { const XbState xs = xcd_barrier_arrive(bar);
;       const int bx0 = (int)blockIdx.x, G0 = (int)gridDim.x, vcu0 = (G0 % 8 == 0) ? (bx0 % 8) * (G0 / 8) + bx0 / 8 : bx0;
;       const int gw0 = vcu0 * NWAVES + (int)(threadIdx.x >> 6); unsigned ln = threadIdx.x & 63u; asm volatile("" : "+v"(ln));
;       const float* xr = args.in[0] + (size_t)(gw0 < MP ? gw0 : 0) * DM;
; #pragma unroll
;       for (int j = 0; j < 8; ++j) { xpre[2 * j] = ldg<f32x4>(xr, (128u * j + 2u * ln) * 16u); xpre[2 * j + 1] = ldg<f32x4>(xr, (128u * j + 2u * ln + 1u) * 16u); }
;       xcd_barrier_wait(bar, xs); }
.LBB0_801:
	v_lshrrev_b32_e32 v1, 6, v0
	v_lshl_or_b32 v1, s6, 3, v1
	s_movk_i32 s12, 0x2000
	s_load_dwordx2 s[6:7], s[0:1], 0x0
	v_cmp_gt_i32_e32 vcc, s12, v1
	v_and_b32_e32 v4, 63, v0
	v_mov_b32_e32 v5, 0
	s_waitcnt lgkmcnt(0)
	v_cndmask_b32_e32 v2, 0, v1, vcc
	v_ashrrev_i32_e32 v3, 31, v2
	v_lshlrev_b64 v[2:3], 14, v[2:3]
	v_lshl_add_u64 v[2:3], s[6:7], 0, v[2:3]
	v_lshlrev_b32_e32 v4, 5, v4
	v_lshl_add_u64 v[6:7], v[2:3], 0, v[4:5]
	global_load_dwordx4 v[18:21], v[6:7], off offset:16
	global_load_dwordx4 v[26:29], v[6:7], off
	v_add_u32_e32 v6, 0x800, v4
	v_mov_b32_e32 v7, v5
	v_lshl_add_u64 v[6:7], v[2:3], 0, v[6:7]
	global_load_dwordx4 v[22:25], v[6:7], off offset:16
	global_load_dwordx4 v[34:37], v[6:7], off
	v_add_u32_e32 v6, 0x1000, v4
	v_mov_b32_e32 v7, v5
	v_lshl_add_u64 v[6:7], v[2:3], 0, v[6:7]
	global_load_dwordx4 v[30:33], v[6:7], off offset:16
	global_load_dwordx4 v[46:49], v[6:7], off
	v_add_u32_e32 v6, 0x1800, v4
	v_mov_b32_e32 v7, v5
	v_lshl_add_u64 v[6:7], v[2:3], 0, v[6:7]
	global_load_dwordx4 v[38:41], v[6:7], off offset:16
	global_load_dwordx4 v[54:57], v[6:7], off
	v_add_u32_e32 v6, 0x2000, v4
	v_mov_b32_e32 v7, v5
	v_lshl_add_u64 v[6:7], v[2:3], 0, v[6:7]
	global_load_dwordx4 v[50:53], v[6:7], off offset:16
	global_load_dwordx4 v[58:61], v[6:7], off
	v_add_u32_e32 v6, 0x2800, v4
	v_mov_b32_e32 v7, v5
	v_lshl_add_u64 v[6:7], v[2:3], 0, v[6:7]
	global_load_dwordx4 v[42:45], v[6:7], off offset:16
	global_load_dwordx4 v[62:65], v[6:7], off
	v_add_u32_e32 v6, 0x3000, v4
	v_mov_b32_e32 v7, v5
	v_add_u32_e32 v4, 0x3800, v4
	v_lshl_add_u64 v[6:7], v[2:3], 0, v[6:7]
	v_lshl_add_u64 v[68:69], v[2:3], 0, v[4:5]
	global_load_dwordx4 v[10:13], v[6:7], off offset:16
	global_load_dwordx4 v[14:17], v[6:7], off
	global_load_dwordx4 v[2:5], v[68:69], off offset:16
	s_nop 0
	global_load_dwordx4 v[6:9], v[68:69], off
	s_and_saveexec_b64 s[6:7], s[14:15]
	s_cbranch_execz .LBB0_831
	v_mov_b32_e32 v1, 0x7000
	s_mov_b32 s16, 0
.Lbar5_poll:
	global_load_dword v67, v1, s[30:31] offset:1024 sc1
	s_waitcnt vmcnt(0)
	v_cmp_ge_u32_e32 vcc, v67, v66
	s_cbranch_vccnz .Lbar5_go
	s_sleep 1
	s_add_u32 s16, s16, 1
	s_cmp_lt_u32 s16, 0x8000
	s_cbranch_scc1 .Lbar5_poll
